# v22: v19 + compression second-layer (postproc_b) row loop: its 10 partial-sum loads issued together with one wait instead of 8 serialized round trips
# speedup vs baseline: 1.0032x; 1.0012x over previous
; #define LAS __attribute__((address_space(3)))
; __device__ __forceinline__ unsigned f2bf(float f) { unsigned u = __builtin_bit_cast(unsigned, f); return (u + 0x7fffu + ((u >> 16) & 1u)) >> 16; }
; __device__ __forceinline__ float silu_f(float g) { return g * __builtin_amdgcn_rcpf(1.0f + fast_exp2(-g * LOG2E)); }
; __device__ __forceinline__ void postproc_b(const Params& p, LAS unsigned char* lds, int l, int gw, int ngw, int lane) {
;     ...
;     for (int r = gw; r < 8192; r += ngw) {
;         const int kv = r >> 12, rr = r & 4095, i = rr & 255;
;         const LAS float* w2 = w2l + kv * 128 * 64 + lane;
;         float hs0 = CMPB[(l * 2 + kv) * 128 + lane], hs1 = CMPB[(l * 2 + kv) * 128 + 64 + lane];
; #pragma unroll
;         for (int sl = 0; sl < 4; ++sl) { hs0 += HIDP[((size_t)sl * 8192 + r) * 128 + lane]; hs1 += HIDP[((size_t)sl * 8192 + r) * 128 + 64 + lane]; }
;         const int h0 = __builtin_bit_cast(int, bf2f(f2bf(silu_f(hs0)))), h1 = __builtin_bit_cast(int, bf2f(f2bf(silu_f(hs1))));
;         float a = 0.f;
; #pragma unroll
;         for (int k = 0; k < 64; ++k) a += __builtin_bit_cast(float, __builtin_amdgcn_readlane(h0, k)) * w2[k * 64];
; #pragma unroll
;         for (int k = 0; k < 64; ++k) a += __builtin_bit_cast(float, __builtin_amdgcn_readlane(h1, k)) * w2[(64 + k) * 64];
.LBB0_623:
	s_ashr_i32 s1, s0, 12
	v_lshl_add_u32 v6, s1, 7, v2
	v_ashrrev_i32_e32 v7, 31, v6
	v_lshl_add_u64 v[6:7], v[6:7], 2, s[16:17]
	global_load_dword v18, v[6:7], off
	global_load_dword v19, v[6:7], off offset:256
	global_load_dword v20, v[4:5], off
	global_load_dword v21, v[4:5], off offset:256
	s_mov_b32 s2, 0x400000
	v_add_co_u32_e32 v6, vcc, s2, v4
	s_nop 1
	v_addc_co_u32_e32 v7, vcc, 0, v5, vcc
	global_load_dword v22, v[6:7], off
	global_load_dword v23, v[6:7], off offset:256
	s_mov_b32 s2, 0x800000
	v_add_co_u32_e32 v6, vcc, s2, v4
	s_nop 1
	v_addc_co_u32_e32 v7, vcc, 0, v5, vcc
	global_load_dword v24, v[6:7], off
	global_load_dword v25, v[6:7], off offset:256
	s_mov_b32 s2, 0xc00000
	v_add_co_u32_e32 v6, vcc, s2, v4
	s_nop 1
	v_addc_co_u32_e32 v7, vcc, 0, v5, vcc
	global_load_dword v26, v[6:7], off
	global_load_dword v27, v[6:7], off offset:256
	s_mov_b64 s[12:13], -1
	v_lshl_add_u32 v7, s1, 15, v3
	ds_read2st64_b32 v[10:11], v7 offset1:1
	s_waitcnt vmcnt(0)
	v_add_f32_e32 v8, v18, v20
	v_add_f32_e32 v9, v19, v21
	v_add_f32_e32 v8, v8, v22
	v_add_f32_e32 v9, v9, v23
	v_add_f32_e32 v8, v8, v24
	v_add_f32_e32 v9, v9, v25
	v_add_f32_e32 v8, v8, v26
	v_add_f32_e32 v6, v9, v27
	v_mul_f32_e32 v9, 0xbfb8aa3b, v8
	v_exp_f32_e32 v9, v9
	s_nop 0
	v_add_f32_e32 v9, 1.0, v9
	v_rcp_f32_e32 v9, v9
	s_nop 0
	v_mul_f32_e32 v8, v8, v9
	v_bfe_u32 v9, v8, 16, 1
	v_add3_u32 v8, v8, v9, s79
	v_mul_f32_e32 v9, 0xbfb8aa3b, v6
	v_exp_f32_e32 v9, v9
	v_and_b32_e32 v8, 0xffff0000, v8
	v_add_f32_e32 v9, 1.0, v9
	v_rcp_f32_e32 v9, v9
	v_readlane_b32 s1, v8, 0
	v_mul_f32_e32 v6, v6, v9
	v_bfe_u32 v9, v6, 16, 1
	v_add3_u32 v9, v6, v9, s79
	s_waitcnt lgkmcnt(0)
	v_fma_f32 v6, v10, s1, 0
	v_readlane_b32 s1, v8, 1
	s_nop 1
	v_fmac_f32_e32 v6, s1, v11
	ds_read2st64_b32 v[10:11], v7 offset0:2 offset1:3
	v_readlane_b32 s1, v8, 2
	s_waitcnt lgkmcnt(0)
	s_nop 0
	v_fmac_f32_e32 v6, s1, v10
	v_readlane_b32 s1, v8, 3
	s_nop 1
	v_fmac_f32_e32 v6, s1, v11
	ds_read2st64_b32 v[10:11], v7 offset0:4 offset1:5
	v_readlane_b32 s1, v8, 4
	s_waitcnt lgkmcnt(0)
	s_nop 0
	v_fmac_f32_e32 v6, s1, v10
	v_readlane_b32 s1, v8, 5
	s_nop 1
	v_fmac_f32_e32 v6, s1, v11
	ds_read2st64_b32 v[10:11], v7 offset0:6 offset1:7
	v_readlane_b32 s1, v8, 6
	s_waitcnt lgkmcnt(0)
	s_nop 0
	v_fmac_f32_e32 v6, s1, v10
	v_readlane_b32 s1, v8, 7
	s_nop 1
	v_fmac_f32_e32 v6, s1, v11
	ds_read2st64_b32 v[10:11], v7 offset0:8 offset1:9
	v_readlane_b32 s1, v8, 8
	s_waitcnt lgkmcnt(0)
	s_nop 0
	v_fmac_f32_e32 v6, s1, v10
	v_readlane_b32 s1, v8, 9
	s_nop 1
	v_fmac_f32_e32 v6, s1, v11
	ds_read2st64_b32 v[10:11], v7 offset0:10 offset1:11
	v_readlane_b32 s1, v8, 10
	s_waitcnt lgkmcnt(0)
	s_nop 0
	v_fmac_f32_e32 v6, s1, v10
	v_readlane_b32 s1, v8, 11
	s_nop 1
	v_fmac_f32_e32 v6, s1, v11
	ds_read2st64_b32 v[10:11], v7 offset0:12 offset1:13
	v_readlane_b32 s1, v8, 12
	s_waitcnt lgkmcnt(0)
	s_nop 0
	v_fmac_f32_e32 v6, s1, v10
	v_readlane_b32 s1, v8, 13
	s_nop 1
	v_fmac_f32_e32 v6, s1, v11
	ds_read2st64_b32 v[10:11], v7 offset0:14 offset1:15
	v_readlane_b32 s1, v8, 14
	s_waitcnt lgkmcnt(0)
	s_nop 0
	v_fmac_f32_e32 v6, s1, v10
	v_readlane_b32 s1, v8, 15
	s_nop 1
	v_fmac_f32_e32 v6, s1, v11
	ds_read2st64_b32 v[10:11], v7 offset0:16 offset1:17
	v_readlane_b32 s1, v8, 16
	s_waitcnt lgkmcnt(0)
	s_nop 0
	v_fmac_f32_e32 v6, s1, v10
	v_readlane_b32 s1, v8, 17
	s_nop 1
	v_fmac_f32_e32 v6, s1, v11
	ds_read2st64_b32 v[10:11], v7 offset0:18 offset1:19
	v_readlane_b32 s1, v8, 18
	s_waitcnt lgkmcnt(0)
	s_nop 0
	v_fmac_f32_e32 v6, s1, v10
	v_readlane_b32 s1, v8, 19
	s_nop 1
	v_fmac_f32_e32 v6, s1, v11
	ds_read2st64_b32 v[10:11], v7 offset0:20 offset1:21
	v_readlane_b32 s1, v8, 20
	s_waitcnt lgkmcnt(0)
	s_nop 0
	v_fmac_f32_e32 v6, s1, v10
	v_readlane_b32 s1, v8, 21
	s_nop 1
	v_fmac_f32_e32 v6, s1, v11
	ds_read2st64_b32 v[10:11], v7 offset0:22 offset1:23
	v_readlane_b32 s1, v8, 22
	s_waitcnt lgkmcnt(0)
	s_nop 0
	v_fmac_f32_e32 v6, s1, v10
	v_readlane_b32 s1, v8, 23
	s_nop 1
	v_fmac_f32_e32 v6, s1, v11
	ds_read2st64_b32 v[10:11], v7 offset0:24 offset1:25
	v_readlane_b32 s1, v8, 24
	s_waitcnt lgkmcnt(0)
	s_nop 0
	v_fmac_f32_e32 v6, s1, v10
	v_readlane_b32 s1, v8, 25
	s_nop 1
	v_fmac_f32_e32 v6, s1, v11
	ds_read2st64_b32 v[10:11], v7 offset0:26 offset1:27
	v_readlane_b32 s1, v8, 26
	s_waitcnt lgkmcnt(0)
	s_nop 0
	v_fmac_f32_e32 v6, s1, v10
	v_readlane_b32 s1, v8, 27
	s_nop 1
	v_fmac_f32_e32 v6, s1, v11
	ds_read2st64_b32 v[10:11], v7 offset0:28 offset1:29
	v_readlane_b32 s1, v8, 28
	s_waitcnt lgkmcnt(0)
	s_nop 0
	v_fmac_f32_e32 v6, s1, v10
	v_readlane_b32 s1, v8, 29
	s_nop 1
	v_fmac_f32_e32 v6, s1, v11
	ds_read2st64_b32 v[10:11], v7 offset0:30 offset1:31
	v_readlane_b32 s1, v8, 30
	s_waitcnt lgkmcnt(0)
	s_nop 0
	v_fmac_f32_e32 v6, s1, v10
	v_readlane_b32 s1, v8, 31
	s_nop 1
	v_fmac_f32_e32 v6, s1, v11
	ds_read2st64_b32 v[10:11], v7 offset0:32 offset1:33
	v_readlane_b32 s1, v8, 32
	s_waitcnt lgkmcnt(0)
	s_nop 0
	v_fmac_f32_e32 v6, s1, v10
	v_readlane_b32 s1, v8, 33
	s_nop 1
	v_fmac_f32_e32 v6, s1, v11
	ds_read2st64_b32 v[10:11], v7 offset0:34 offset1:35
	v_readlane_b32 s1, v8, 34
	s_waitcnt lgkmcnt(0)
	s_nop 0
	v_fmac_f32_e32 v6, s1, v10
	v_readlane_b32 s1, v8, 35
	s_nop 1
	v_fmac_f32_e32 v6, s1, v11
	ds_read2st64_b32 v[10:11], v7 offset0:36 offset1:37
	v_readlane_b32 s1, v8, 36
	s_waitcnt lgkmcnt(0)
	s_nop 0
	v_fmac_f32_e32 v6, s1, v10
	v_readlane_b32 s1, v8, 37
	s_nop 1
	v_fmac_f32_e32 v6, s1, v11
	ds_read2st64_b32 v[10:11], v7 offset0:38 offset1:39
	v_readlane_b32 s1, v8, 38
	s_waitcnt lgkmcnt(0)
	s_nop 0
	v_fmac_f32_e32 v6, s1, v10
	v_readlane_b32 s1, v8, 39
	s_nop 1
	v_fmac_f32_e32 v6, s1, v11
	ds_read2st64_b32 v[10:11], v7 offset0:40 offset1:41
	v_readlane_b32 s1, v8, 40
	s_waitcnt lgkmcnt(0)
; __device__ __forceinline__ void postproc_b(const Params& p, LAS unsigned char* lds, int l, int gw, int ngw, int lane) {
;     ...
;         for (int k = 0; k < 64; ++k) a += __builtin_bit_cast(float, __builtin_amdgcn_readlane(h0, k)) * w2[k * 64];
; #pragma unroll
;         for (int k = 0; k < 64; ++k) a += __builtin_bit_cast(float, __builtin_amdgcn_readlane(h1, k)) * w2[(64 + k) * 64];
	s_nop 0
	v_fmac_f32_e32 v6, s1, v10
	v_readlane_b32 s1, v8, 41
	s_nop 1
	v_fmac_f32_e32 v6, s1, v11
	ds_read2st64_b32 v[10:11], v7 offset0:42 offset1:43
	v_readlane_b32 s1, v8, 42
	s_waitcnt lgkmcnt(0)
	s_nop 0
	v_fmac_f32_e32 v6, s1, v10
	v_readlane_b32 s1, v8, 43
	s_nop 1
	v_fmac_f32_e32 v6, s1, v11
	ds_read2st64_b32 v[10:11], v7 offset0:44 offset1:45
	v_readlane_b32 s1, v8, 44
	s_waitcnt lgkmcnt(0)
	s_nop 0
	v_fmac_f32_e32 v6, s1, v10
	v_readlane_b32 s1, v8, 45
	s_nop 1
	v_fmac_f32_e32 v6, s1, v11
	ds_read2st64_b32 v[10:11], v7 offset0:46 offset1:47
	v_readlane_b32 s1, v8, 46
	s_waitcnt lgkmcnt(0)
	s_nop 0
	v_fmac_f32_e32 v6, s1, v10
	v_readlane_b32 s1, v8, 47
	s_nop 1
	v_fmac_f32_e32 v6, s1, v11
	ds_read2st64_b32 v[10:11], v7 offset0:48 offset1:49
	v_readlane_b32 s1, v8, 48
	s_waitcnt lgkmcnt(0)
	s_nop 0
	v_fmac_f32_e32 v6, s1, v10
	v_readlane_b32 s1, v8, 49
	s_nop 1
	v_fmac_f32_e32 v6, s1, v11
	ds_read2st64_b32 v[10:11], v7 offset0:50 offset1:51
	v_readlane_b32 s1, v8, 50
	s_waitcnt lgkmcnt(0)
	s_nop 0
	v_fmac_f32_e32 v6, s1, v10
	v_readlane_b32 s1, v8, 51
	s_nop 1
	v_fmac_f32_e32 v6, s1, v11
	ds_read2st64_b32 v[10:11], v7 offset0:52 offset1:53
	v_readlane_b32 s1, v8, 52
	s_waitcnt lgkmcnt(0)
	s_nop 0
	v_fmac_f32_e32 v6, s1, v10
	v_readlane_b32 s1, v8, 53
	s_nop 1
	v_fmac_f32_e32 v6, s1, v11
	ds_read2st64_b32 v[10:11], v7 offset0:54 offset1:55
	v_readlane_b32 s1, v8, 54
	s_waitcnt lgkmcnt(0)
	s_nop 0
	v_fmac_f32_e32 v6, s1, v10
	v_readlane_b32 s1, v8, 55
	s_nop 1
	v_fmac_f32_e32 v6, s1, v11
	ds_read2st64_b32 v[10:11], v7 offset0:56 offset1:57
	v_readlane_b32 s1, v8, 56
	s_waitcnt lgkmcnt(0)
	s_nop 0
	v_fmac_f32_e32 v6, s1, v10
	v_readlane_b32 s1, v8, 57
	s_nop 1
	v_fmac_f32_e32 v6, s1, v11
	ds_read2st64_b32 v[10:11], v7 offset0:58 offset1:59
	v_readlane_b32 s1, v8, 58
	s_waitcnt lgkmcnt(0)
	s_nop 0
	v_fmac_f32_e32 v6, s1, v10
	v_readlane_b32 s1, v8, 59
	s_nop 1
	v_fmac_f32_e32 v6, s1, v11
	ds_read2st64_b32 v[10:11], v7 offset0:60 offset1:61
	v_readlane_b32 s1, v8, 60
	s_waitcnt lgkmcnt(0)
	s_nop 0
	v_fmac_f32_e32 v6, s1, v10
	v_readlane_b32 s1, v8, 61
	s_nop 1
	v_fmac_f32_e32 v6, s1, v11
	ds_read2st64_b32 v[10:11], v7 offset0:62 offset1:63
	v_readlane_b32 s1, v8, 62
	s_waitcnt lgkmcnt(0)
	s_nop 0
	v_fmac_f32_e32 v6, s1, v10
	v_readlane_b32 s1, v8, 63
	v_and_b32_e32 v8, 0xffff0000, v9
	s_nop 0
	v_fmac_f32_e32 v6, s1, v11
	ds_read2st64_b32 v[10:11], v7 offset0:64 offset1:65
	v_readlane_b32 s1, v8, 0
	s_waitcnt lgkmcnt(0)
	s_nop 0
	v_fmac_f32_e32 v6, s1, v10
	v_readlane_b32 s1, v8, 1
	s_nop 1
	v_fmac_f32_e32 v6, s1, v11
	ds_read2st64_b32 v[10:11], v7 offset0:66 offset1:67
	v_readlane_b32 s1, v8, 2
	s_waitcnt lgkmcnt(0)
	s_nop 0
	v_fmac_f32_e32 v6, s1, v10
	v_readlane_b32 s1, v8, 3
	s_nop 1
	v_fmac_f32_e32 v6, s1, v11
	ds_read2st64_b32 v[10:11], v7 offset0:68 offset1:69
	v_readlane_b32 s1, v8, 4
	s_waitcnt lgkmcnt(0)
	s_nop 0
	v_fmac_f32_e32 v6, s1, v10
	v_readlane_b32 s1, v8, 5
	s_nop 1
	v_fmac_f32_e32 v6, s1, v11
	ds_read2st64_b32 v[10:11], v7 offset0:70 offset1:71
	v_readlane_b32 s1, v8, 6
	s_waitcnt lgkmcnt(0)
	s_nop 0
	v_fmac_f32_e32 v6, s1, v10
	v_readlane_b32 s1, v8, 7
	s_nop 1
	v_fmac_f32_e32 v6, s1, v11
	ds_read2st64_b32 v[10:11], v7 offset0:72 offset1:73
	v_readlane_b32 s1, v8, 8
	s_waitcnt lgkmcnt(0)
	s_nop 0
	v_fmac_f32_e32 v6, s1, v10
	v_readlane_b32 s1, v8, 9
	s_nop 1
	v_fmac_f32_e32 v6, s1, v11
	ds_read2st64_b32 v[10:11], v7 offset0:74 offset1:75
	v_readlane_b32 s1, v8, 10
	s_waitcnt lgkmcnt(0)
	s_nop 0
	v_fmac_f32_e32 v6, s1, v10
	v_readlane_b32 s1, v8, 11
	s_nop 1
	v_fmac_f32_e32 v6, s1, v11
	ds_read2st64_b32 v[10:11], v7 offset0:76 offset1:77
	v_readlane_b32 s1, v8, 12
	s_waitcnt lgkmcnt(0)
	s_nop 0
	v_fmac_f32_e32 v6, s1, v10
	v_readlane_b32 s1, v8, 13
	s_nop 1
	v_fmac_f32_e32 v6, s1, v11
	ds_read2st64_b32 v[10:11], v7 offset0:78 offset1:79
	v_readlane_b32 s1, v8, 14
	s_waitcnt lgkmcnt(0)
	s_nop 0
	v_fmac_f32_e32 v6, s1, v10
	v_readlane_b32 s1, v8, 15
	s_nop 1
	v_fmac_f32_e32 v6, s1, v11
	ds_read2st64_b32 v[10:11], v7 offset0:80 offset1:81
	v_readlane_b32 s1, v8, 16
	s_waitcnt lgkmcnt(0)
	s_nop 0
	v_fmac_f32_e32 v6, s1, v10
	v_readlane_b32 s1, v8, 17
	s_nop 1
	v_fmac_f32_e32 v6, s1, v11
	ds_read2st64_b32 v[10:11], v7 offset0:82 offset1:83
	v_readlane_b32 s1, v8, 18
	s_waitcnt lgkmcnt(0)
	s_nop 0
	v_fmac_f32_e32 v6, s1, v10
	v_readlane_b32 s1, v8, 19
	s_nop 1
	v_fmac_f32_e32 v6, s1, v11
	ds_read2st64_b32 v[10:11], v7 offset0:84 offset1:85
	v_readlane_b32 s1, v8, 20
	s_waitcnt lgkmcnt(0)
; __device__ __forceinline__ unsigned f2bf(float f) { unsigned u = __builtin_bit_cast(unsigned, f); return (u + 0x7fffu + ((u >> 16) & 1u)) >> 16; }
; __device__ __forceinline__ void postproc_b(const Params& p, LAS unsigned char* lds, int l, int gw, int ngw, int lane) {
;     ...
;         for (int k = 0; k < 64; ++k) a += __builtin_bit_cast(float, __builtin_amdgcn_readlane(h1, k)) * w2[(64 + k) * 64];
;         if (kv == 0) { float y = a * rsqrtf(wave_sum(a * a) * (1.0f / 64) + EPS) * gck; if (i == 255) y = 0.f; KCMP[(size_t)rr * 64 + lane] = (bf16_t)f2bf(y); }
;         else { if (i == 255) a = 0.f; VCMP[(size_t)rr * 64 + lane] = (bf16_t)f2bf(a); }
	s_nop 0
	v_fmac_f32_e32 v6, s1, v10
	v_readlane_b32 s1, v8, 21
	s_nop 1
	v_fmac_f32_e32 v6, s1, v11
	ds_read2st64_b32 v[10:11], v7 offset0:86 offset1:87
	v_readlane_b32 s1, v8, 22
	s_waitcnt lgkmcnt(0)
	s_nop 0
	v_fmac_f32_e32 v6, s1, v10
	v_readlane_b32 s1, v8, 23
	s_nop 1
	v_fmac_f32_e32 v6, s1, v11
	ds_read2st64_b32 v[10:11], v7 offset0:88 offset1:89
	v_readlane_b32 s1, v8, 24
	s_waitcnt lgkmcnt(0)
	s_nop 0
	v_fmac_f32_e32 v6, s1, v10
	v_readlane_b32 s1, v8, 25
	s_nop 1
	v_fmac_f32_e32 v6, s1, v11
	ds_read2st64_b32 v[10:11], v7 offset0:90 offset1:91
	v_readlane_b32 s1, v8, 26
	s_waitcnt lgkmcnt(0)
	s_nop 0
	v_fmac_f32_e32 v6, s1, v10
	v_readlane_b32 s1, v8, 27
	s_nop 1
	v_fmac_f32_e32 v6, s1, v11
	ds_read2st64_b32 v[10:11], v7 offset0:92 offset1:93
	v_readlane_b32 s1, v8, 28
	s_waitcnt lgkmcnt(0)
	s_nop 0
	v_fmac_f32_e32 v6, s1, v10
	v_readlane_b32 s1, v8, 29
	s_nop 1
	v_fmac_f32_e32 v6, s1, v11
	ds_read2st64_b32 v[10:11], v7 offset0:94 offset1:95
	v_readlane_b32 s1, v8, 30
	s_waitcnt lgkmcnt(0)
	s_nop 0
	v_fmac_f32_e32 v6, s1, v10
	v_readlane_b32 s1, v8, 31
	s_nop 1
	v_fmac_f32_e32 v6, s1, v11
	ds_read2st64_b32 v[10:11], v7 offset0:96 offset1:97
	v_readlane_b32 s1, v8, 32
	s_waitcnt lgkmcnt(0)
	s_nop 0
	v_fmac_f32_e32 v6, s1, v10
	v_readlane_b32 s1, v8, 33
	s_nop 1
	v_fmac_f32_e32 v6, s1, v11
	ds_read2st64_b32 v[10:11], v7 offset0:98 offset1:99
	v_readlane_b32 s1, v8, 34
	s_waitcnt lgkmcnt(0)
	s_nop 0
	v_fmac_f32_e32 v6, s1, v10
	v_readlane_b32 s1, v8, 35
	s_nop 1
	v_fmac_f32_e32 v6, s1, v11
	ds_read2st64_b32 v[10:11], v7 offset0:100 offset1:101
	v_readlane_b32 s1, v8, 36
	s_waitcnt lgkmcnt(0)
	s_nop 0
	v_fmac_f32_e32 v6, s1, v10
	v_readlane_b32 s1, v8, 37
	s_nop 1
	v_fmac_f32_e32 v6, s1, v11
	ds_read2st64_b32 v[10:11], v7 offset0:102 offset1:103
	v_readlane_b32 s1, v8, 38
	s_waitcnt lgkmcnt(0)
	s_nop 0
	v_fmac_f32_e32 v6, s1, v10
	v_readlane_b32 s1, v8, 39
	s_nop 1
	v_fmac_f32_e32 v6, s1, v11
	ds_read2st64_b32 v[10:11], v7 offset0:104 offset1:105
	v_readlane_b32 s1, v8, 40
	s_waitcnt lgkmcnt(0)
	s_nop 0
	v_fmac_f32_e32 v6, s1, v10
	v_readlane_b32 s1, v8, 41
	s_nop 1
	v_fmac_f32_e32 v6, s1, v11
	ds_read2st64_b32 v[10:11], v7 offset0:106 offset1:107
	v_readlane_b32 s1, v8, 42
	s_waitcnt lgkmcnt(0)
	s_nop 0
	v_fmac_f32_e32 v6, s1, v10
	v_readlane_b32 s1, v8, 43
	s_nop 1
	v_fmac_f32_e32 v6, s1, v11
	ds_read2st64_b32 v[10:11], v7 offset0:108 offset1:109
	v_readlane_b32 s1, v8, 44
	s_waitcnt lgkmcnt(0)
	s_nop 0
	v_fmac_f32_e32 v6, s1, v10
	v_readlane_b32 s1, v8, 45
	s_nop 1
	v_fmac_f32_e32 v6, s1, v11
	ds_read2st64_b32 v[10:11], v7 offset0:110 offset1:111
	v_readlane_b32 s1, v8, 46
	s_waitcnt lgkmcnt(0)
	s_nop 0
	v_fmac_f32_e32 v6, s1, v10
	v_readlane_b32 s1, v8, 47
	s_nop 1
	v_fmac_f32_e32 v6, s1, v11
	ds_read2st64_b32 v[10:11], v7 offset0:112 offset1:113
	v_readlane_b32 s1, v8, 48
	s_waitcnt lgkmcnt(0)
	s_nop 0
	v_fmac_f32_e32 v6, s1, v10
	v_readlane_b32 s1, v8, 49
	s_nop 1
	v_fmac_f32_e32 v6, s1, v11
	ds_read2st64_b32 v[10:11], v7 offset0:114 offset1:115
	v_readlane_b32 s1, v8, 50
	s_waitcnt lgkmcnt(0)
	s_nop 0
	v_fmac_f32_e32 v6, s1, v10
	v_readlane_b32 s1, v8, 51
	s_nop 1
	v_fmac_f32_e32 v6, s1, v11
	ds_read2st64_b32 v[10:11], v7 offset0:116 offset1:117
	v_readlane_b32 s1, v8, 52
	s_waitcnt lgkmcnt(0)
	s_nop 0
	v_fmac_f32_e32 v6, s1, v10
	v_readlane_b32 s1, v8, 53
	s_nop 1
	v_fmac_f32_e32 v6, s1, v11
	ds_read2st64_b32 v[10:11], v7 offset0:118 offset1:119
	v_readlane_b32 s1, v8, 54
	s_waitcnt lgkmcnt(0)
	s_nop 0
	v_fmac_f32_e32 v6, s1, v10
	v_readlane_b32 s1, v8, 55
	s_nop 1
	v_fmac_f32_e32 v6, s1, v11
	ds_read2st64_b32 v[10:11], v7 offset0:120 offset1:121
	v_readlane_b32 s1, v8, 56
	s_waitcnt lgkmcnt(0)
	s_nop 0
	v_fmac_f32_e32 v6, s1, v10
	v_readlane_b32 s1, v8, 57
	s_nop 1
	v_fmac_f32_e32 v6, s1, v11
	ds_read2st64_b32 v[10:11], v7 offset0:122 offset1:123
	v_readlane_b32 s1, v8, 58
	s_waitcnt lgkmcnt(0)
	s_nop 0
	v_fmac_f32_e32 v6, s1, v10
	v_readlane_b32 s1, v8, 59
	s_nop 1
	v_fmac_f32_e32 v6, s1, v11
	ds_read2st64_b32 v[10:11], v7 offset0:124 offset1:125
	v_readlane_b32 s1, v8, 60
	s_waitcnt lgkmcnt(0)
	s_nop 0
	v_fmac_f32_e32 v6, s1, v10
	v_readlane_b32 s1, v8, 61
	s_nop 1
	v_fmac_f32_e32 v6, s1, v11
	ds_read2st64_b32 v[10:11], v7 offset0:126 offset1:127
	v_readlane_b32 s1, v8, 62
	s_waitcnt lgkmcnt(0)
	s_nop 0
	v_fmac_f32_e32 v6, s1, v10
	v_readlane_b32 s1, v8, 63
	s_nop 1
	v_fmac_f32_e32 v6, s1, v11
	s_and_b32 s1, s0, 0xff
	s_cmpk_gt_u32 s0, 0xfff
	s_cbranch_scc0 .LBB0_625
	s_cmpk_lg_i32 s1, 0xff
	s_cselect_b64 vcc, -1, 0
	v_cndmask_b32_e32 v7, 0, v6, vcc
	v_bfe_u32 v8, v7, 16, 1
	s_and_b32 s2, s14, 0x3ffc0
	v_add3_u32 v7, v7, v8, s79
	s_mov_b64 s[12:13], 0
	v_mov_b32_e32 v8, s2
